# attention tile loop: K/V LDS staging writes moved into the PV MFMA tail; first QK LDS reads issued before next-tile global loads
# speedup vs baseline: 1.0011x; 1.0011x over previous
.LBB0_298:
	s_cmp_gt_u32 s97, s15
	s_cbranch_scc1 .Lattn_skip0
	v_add_u32_e32 v0, s40, v206
	ds_read_b128 v[180:183], v211
	ds_read_b128 v[184:187], v219
	ds_read_b128 v[188:191], v0 offset:32
	ds_read_b128 v[236:239], v0 offset:64
	ds_read_b128 v[240:243], v0
	ds_read_b128 v[244:247], v220
	ds_read_b128 v[192:195], v0 offset:96
	ds_read_b128 v[196:199], v221
	s_waitcnt vmcnt(2)
	v_add_co_u32_e32 v6, vcc, 0x20000, v200
	v_lshl_add_u64 v[14:15], v[202:203], 0, s[26:27]
	s_nop 0
	v_addc_co_u32_e32 v7, vcc, 0, v201, vcc
	s_waitcnt vmcnt(1)
	v_add_co_u32_e32 v10, vcc, 0x4000, v14
	global_load_dwordx4 v[2:5], v[6:7], off
	s_nop 0
	global_load_dwordx4 v[6:9], v[6:7], off offset:256
	v_addc_co_u32_e32 v11, vcc, 0, v15, vcc
	v_add_co_u32_e32 v160, vcc, 0x6000, v14
	s_nop 0
	v_addc_co_u32_e32 v161, vcc, 0, v15, vcc
	global_load_dwordx4 v[10:13], v[10:11], off
	s_nop 0
	global_load_dwordx4 v[176:179], v[160:161], off
	s_waitcnt lgkmcnt(3)
	v_mfma_f32_32x32x16_bf16 v[160:175], v[240:243], v[180:183], v[144:159]
	ds_read_b128 v[180:183], v0 offset:128
	ds_read_b128 v[240:243], v222
	v_mfma_f32_32x32x16_bf16 v[160:175], v[188:191], v[184:187], v[160:175]
	ds_read_b128 v[184:187], v0 offset:160
	ds_read_b128 v[188:191], v223
	s_waitcnt lgkmcnt(6)
	v_mfma_f32_32x32x16_bf16 v[160:175], v[236:239], v[244:247], v[160:175]
	ds_read_b128 v[236:239], v0 offset:192
	ds_read_b128 v[244:247], v224
	s_waitcnt lgkmcnt(6)
	v_mfma_f32_32x32x16_bf16 v[160:175], v[192:195], v[196:199], v[160:175]
	ds_read_b128 v[192:195], v0 offset:224
	ds_read_b128 v[196:199], v225
	s_waitcnt lgkmcnt(6)
	v_mfma_f32_32x32x16_bf16 v[160:175], v[180:183], v[240:243], v[160:175]
	s_waitcnt lgkmcnt(4)
	v_mfma_f32_32x32x16_bf16 v[160:175], v[184:187], v[188:191], v[160:175]
	s_waitcnt lgkmcnt(2)
	v_mfma_f32_32x32x16_bf16 v[160:175], v[236:239], v[244:247], v[160:175]
	s_waitcnt lgkmcnt(0)
	v_mfma_f32_32x32x16_bf16 v[160:175], v[192:195], v[196:199], v[160:175]
	ds_read_b128 v[188:191], v218 offset:17408
	ds_read_b128 v[184:187], v218 offset:17440
	ds_read_b128 v[180:183], v218 offset:19968
	s_cmp_lg_u32 s90, s26
	s_cbranch_scc1 .LBB0_301
	s_nop 6
	v_cndmask_b32_e64 v0, v160, v215, s[42:43]
	v_cndmask_b32_e64 v160, v0, v160, s[44:45]
	v_cndmask_b32_e64 v0, v164, v215, s[50:51]
	v_cndmask_b32_e64 v164, v0, v164, s[52:53]
	v_cndmask_b32_e64 v0, v168, v215, s[58:59]
	v_cndmask_b32_e64 v168, v0, v168, s[60:61]
	v_cndmask_b32_e64 v0, v172, v215, s[66:67]
	v_cndmask_b32_e64 v161, v215, v161, s[44:45]
	v_cndmask_b32_e64 v162, v162, v215, s[46:47]
	v_cndmask_b32_e64 v163, v163, v215, s[48:49]
	v_cndmask_b32_e64 v165, v215, v165, s[52:53]
	v_cndmask_b32_e64 v166, v166, v215, s[54:55]
	v_cndmask_b32_e64 v167, v167, v215, s[56:57]
	v_cndmask_b32_e64 v169, v215, v169, s[60:61]
	v_cndmask_b32_e64 v170, v170, v215, s[62:63]
	v_cndmask_b32_e64 v171, v171, v215, s[64:65]
	v_cndmask_b32_e64 v173, v215, v173, s[68:69]
	v_cndmask_b32_e64 v172, v0, v172, s[68:69]
	v_cndmask_b32_e64 v174, v174, v215, s[70:71]
	v_cndmask_b32_e64 v175, v175, v215, s[72:73]

.LBB0_307:
	v_exp_f32_e32 v0, v160
	v_exp_f32_e32 v160, v161
	v_exp_f32_e32 v161, v162
	v_exp_f32_e32 v162, v163
	v_add_f32_e32 v163, 0, v0
	v_exp_f32_e32 v164, v164
	v_add_f32_e32 v163, v160, v163
	v_exp_f32_e32 v165, v165
	v_add_f32_e32 v163, v161, v163
	v_exp_f32_e32 v166, v166
	v_add_f32_e32 v163, v162, v163
	v_exp_f32_e32 v167, v167
	v_add_f32_e32 v163, v164, v163
	v_exp_f32_e32 v168, v168
	v_add_f32_e32 v163, v165, v163
	v_exp_f32_e32 v169, v169
	v_add_f32_e32 v163, v166, v163
	v_exp_f32_e32 v170, v170
	v_add_f32_e32 v163, v167, v163
	v_exp_f32_e32 v171, v171
	v_add_f32_e32 v163, v168, v163
	v_exp_f32_e32 v172, v172
	v_add_f32_e32 v163, v169, v163
	v_exp_f32_e32 v173, v173
	v_add_f32_e32 v163, v170, v163
	v_exp_f32_e32 v174, v174
	v_add_f32_e32 v163, v171, v163
	v_exp_f32_e32 v175, v175
	v_add_f32_e32 v163, v172, v163
	v_add_f32_e32 v163, v173, v163
	v_add_f32_e32 v163, v174, v163
	v_add_f32_e32 v192, v175, v163
	v_cvt_pk_bf16_f32 v160, v0, v160
	v_cvt_pk_bf16_f32 v161, v161, v162
	v_cvt_pk_bf16_f32 v162, v164, v165
	v_cvt_pk_bf16_f32 v163, v166, v167
	v_cvt_pk_bf16_f32 v164, v168, v169
	v_cvt_pk_bf16_f32 v165, v170, v171
	v_cvt_pk_bf16_f32 v166, v172, v173
	v_cvt_pk_bf16_f32 v167, v174, v175
	ds_read_b128 v[168:171], v218 offset:20000
	s_waitcnt lgkmcnt(3)
	v_mfma_f32_32x32x16_bf16 v[128:143], v[188:191], v[160:163], v[128:143]
	ds_read_b128 v[172:175], v218 offset:22528
	s_waitcnt lgkmcnt(3)
	v_mfma_f32_32x32x16_bf16 v[128:143], v[184:187], v[164:167], v[128:143]
	ds_read_b128 v[184:187], v218 offset:22560
	s_waitcnt lgkmcnt(3)
	v_mfma_f32_32x32x16_bf16 v[112:127], v[180:183], v[160:163], v[112:127]
	ds_read_b128 v[180:183], v218 offset:25088
	s_waitcnt lgkmcnt(3)
	v_mfma_f32_32x32x16_bf16 v[112:127], v[168:171], v[164:167], v[112:127]
	ds_read_b128 v[168:171], v218 offset:25120
	s_waitcnt lgkmcnt(3)
	v_mfma_f32_32x32x16_bf16 v[96:111], v[172:175], v[160:163], v[96:111]
	ds_read_b128 v[172:175], v218 offset:27648
	s_waitcnt lgkmcnt(3)
	v_mfma_f32_32x32x16_bf16 v[96:111], v[184:187], v[164:167], v[96:111]
	ds_read_b128 v[184:187], v218 offset:27680
	s_waitcnt lgkmcnt(3)
	v_mfma_f32_32x32x16_bf16 v[80:95], v[180:183], v[160:163], v[80:95]
	ds_read_b128 v[180:183], v218 offset:30208
	s_waitcnt lgkmcnt(3)
	v_mfma_f32_32x32x16_bf16 v[80:95], v[168:171], v[164:167], v[80:95]
	ds_read_b128 v[168:171], v218 offset:30240
	s_waitcnt lgkmcnt(3)
	v_mfma_f32_32x32x16_bf16 v[64:79], v[172:175], v[160:163], v[64:79]
	ds_read_b128 v[172:175], v218 offset:32768
	s_waitcnt lgkmcnt(3)
	v_mfma_f32_32x32x16_bf16 v[64:79], v[184:187], v[164:167], v[64:79]
	ds_read_b128 v[184:187], v218 offset:32800
	s_waitcnt lgkmcnt(3)
	v_mfma_f32_32x32x16_bf16 v[48:63], v[180:183], v[160:163], v[48:63]
	ds_read_b128 v[180:183], v218 offset:35328
	s_waitcnt lgkmcnt(3)
	v_mfma_f32_32x32x16_bf16 v[48:63], v[168:171], v[164:167], v[48:63]
	ds_read_b128 v[168:171], v218 offset:35360
	s_waitcnt vmcnt(3)
	ds_write_b128 v207, v[2:5] offset:37888
	s_waitcnt vmcnt(2)
	ds_write_b128 v207, v[6:9] offset:46592
	s_waitcnt vmcnt(1)
	ds_write2_b64 v210, v[10:11], v[12:13] offset1:2
	s_waitcnt vmcnt(0)
	ds_write2_b64 v234, v[176:177], v[178:179] offset1:2
	s_waitcnt lgkmcnt(7)
	v_mfma_f32_32x32x16_bf16 v[32:47], v[172:175], v[160:163], v[32:47]
	s_waitcnt lgkmcnt(6)
	v_mfma_f32_32x32x16_bf16 v[32:47], v[184:187], v[164:167], v[32:47]
	s_waitcnt lgkmcnt(5)
	v_mfma_f32_32x32x16_bf16 v[16:31], v[180:183], v[160:163], v[16:31]
	s_waitcnt lgkmcnt(4)
	v_mfma_f32_32x32x16_bf16 v[16:31], v[168:171], v[164:167], v[16:31]
	v_add_f32_e32 v235, v235, v192
	s_add_i32 s78, s97, 2
	s_cmp_lt_u32 s78, s77
	s_cselect_b64 s[94:95], -1, 0
	s_cmp_ge_u32 s78, s77
	s_cselect_b64 s[30:31], -1, 0
	s_and_b64 vcc, exec, s[30:31]
	s_branch .Lattn_w0_done
.Lattn_skip0:
	s_waitcnt vmcnt(2)
	v_add_co_u32_e32 v6, vcc, 0x20000, v200
	v_lshl_add_u64 v[14:15], v[202:203], 0, s[26:27]
	s_nop 0
	v_addc_co_u32_e32 v7, vcc, 0, v201, vcc
	s_waitcnt vmcnt(1)
	v_add_co_u32_e32 v10, vcc, 0x4000, v14
	global_load_dwordx4 v[2:5], v[6:7], off
	s_nop 0
	global_load_dwordx4 v[6:9], v[6:7], off offset:256
	v_addc_co_u32_e32 v11, vcc, 0, v15, vcc
	v_add_co_u32_e32 v160, vcc, 0x6000, v14
	s_nop 0
	v_addc_co_u32_e32 v161, vcc, 0, v15, vcc
	global_load_dwordx4 v[10:13], v[10:11], off
	s_nop 0
	global_load_dwordx4 v[176:179], v[160:161], off
	s_add_i32 s78, s97, 2
	s_cmp_lt_u32 s78, s77
	s_cselect_b64 s[94:95], -1, 0
	s_cmp_ge_u32 s78, s77
	s_cselect_b64 s[30:31], -1, 0
	s_and_b64 vcc, exec, s[30:31]
	s_waitcnt vmcnt(3)
	ds_write_b128 v207, v[2:5] offset:37888
	s_waitcnt vmcnt(2)
	ds_write_b128 v207, v[6:9] offset:46592
	s_waitcnt vmcnt(1)
	ds_write2_b64 v210, v[10:11], v[12:13] offset1:2
	s_waitcnt vmcnt(0)
	ds_write2_b64 v234, v[176:177], v[178:179] offset1:2
.Lattn_w0_done:
	s_waitcnt lgkmcnt(0)
	s_barrier
	s_cbranch_vccz .LBB0_314
	s_cmp_ge_u32 s97, s15
	s_cbranch_scc0 .LBB0_315
	s_branch .LBB0_312
.LBB0_314:
	s_cmp_ge_u32 s97, s15
	s_cbranch_scc1 .Lattn_skip1
	ds_read_b128 v[180:183], v211
	ds_read_b128 v[184:187], v219
	ds_read_b128 v[188:191], v233 offset:37920
	ds_read_b128 v[192:195], v233 offset:37952
	ds_read_b128 v[196:199], v233 offset:37888
	ds_read_b128 v[236:239], v220
	ds_read_b128 v[240:243], v233 offset:37984
	ds_read_b128 v[244:247], v221
	v_add_co_u32_e32 v6, vcc, 0x40000, v200
	s_nop 1
	v_addc_co_u32_e32 v7, vcc, 0, v201, vcc
	v_add_co_u32_e32 v10, vcc, 0x8000, v14
	global_load_dwordx4 v[2:5], v[6:7], off
	s_nop 0
	global_load_dwordx4 v[6:9], v[6:7], off offset:256
	v_addc_co_u32_e32 v11, vcc, 0, v15, vcc
	v_add_co_u32_e32 v14, vcc, 0xa000, v14
	s_nop 1
	v_addc_co_u32_e32 v15, vcc, 0, v15, vcc
	global_load_dwordx4 v[10:13], v[10:11], off
	s_nop 0
	global_load_dwordx4 v[176:179], v[14:15], off
	s_branch .Lattn_qk1_rest
.Lattn_skip1:
	v_add_co_u32_e32 v6, vcc, 0x40000, v200
	s_nop 1
	v_addc_co_u32_e32 v7, vcc, 0, v201, vcc
	v_add_co_u32_e32 v10, vcc, 0x8000, v14
	global_load_dwordx4 v[2:5], v[6:7], off
	s_nop 0
	global_load_dwordx4 v[6:9], v[6:7], off offset:256
	v_addc_co_u32_e32 v11, vcc, 0, v15, vcc
	v_add_co_u32_e32 v14, vcc, 0xa000, v14
	s_nop 1
	v_addc_co_u32_e32 v15, vcc, 0, v15, vcc
	global_load_dwordx4 v[10:13], v[10:11], off
	s_nop 0
	global_load_dwordx4 v[176:179], v[14:15], off
	s_branch .LBB0_310

.Lattn_qk1_rest:
	s_waitcnt lgkmcnt(3)
	v_mfma_f32_32x32x16_bf16 v[160:175], v[196:199], v[180:183], v[144:159]
	ds_read_b128 v[180:183], v233 offset:38016
	ds_read_b128 v[196:199], v222
	v_mfma_f32_32x32x16_bf16 v[160:175], v[188:191], v[184:187], v[160:175]
	ds_read_b128 v[184:187], v233 offset:38048
	ds_read_b128 v[188:191], v223
	s_waitcnt lgkmcnt(6)
	v_mfma_f32_32x32x16_bf16 v[160:175], v[192:195], v[236:239], v[160:175]
	ds_read_b128 v[192:195], v233 offset:38080
	ds_read_b128 v[236:239], v224
	s_waitcnt lgkmcnt(6)
	v_mfma_f32_32x32x16_bf16 v[160:175], v[240:243], v[244:247], v[160:175]
	ds_read_b128 v[240:243], v233 offset:38112
	ds_read_b128 v[244:247], v225
	s_waitcnt lgkmcnt(6)
	v_mfma_f32_32x32x16_bf16 v[160:175], v[180:183], v[196:199], v[160:175]
	s_waitcnt lgkmcnt(4)
	v_mfma_f32_32x32x16_bf16 v[160:175], v[184:187], v[188:191], v[160:175]
	s_waitcnt lgkmcnt(2)
	v_mfma_f32_32x32x16_bf16 v[160:175], v[192:195], v[236:239], v[160:175]
	s_waitcnt lgkmcnt(0)
	v_mfma_f32_32x32x16_bf16 v[160:175], v[240:243], v[244:247], v[160:175]
	ds_read_b128 v[188:191], v218 offset:55296
	ds_read_b128 v[184:187], v218 offset:55328
	ds_read_b128 v[180:183], v218 offset:57856
	s_cmp_lg_u32 s96, s26
	s_cbranch_scc1 .LBB0_317
	s_nop 6
	v_cndmask_b32_e64 v0, v160, v215, s[42:43]
	v_cndmask_b32_e64 v160, v0, v160, s[44:45]
	v_cndmask_b32_e64 v0, v164, v215, s[50:51]
	v_cndmask_b32_e64 v164, v0, v164, s[52:53]
	v_cndmask_b32_e64 v0, v168, v215, s[58:59]
	v_cndmask_b32_e64 v168, v0, v168, s[60:61]
	v_cndmask_b32_e64 v0, v172, v215, s[66:67]
	v_cndmask_b32_e64 v161, v215, v161, s[44:45]
	v_cndmask_b32_e64 v162, v162, v215, s[46:47]
	v_cndmask_b32_e64 v163, v163, v215, s[48:49]
	v_cndmask_b32_e64 v165, v215, v165, s[52:53]
	v_cndmask_b32_e64 v166, v166, v215, s[54:55]
	v_cndmask_b32_e64 v167, v167, v215, s[56:57]
	v_cndmask_b32_e64 v169, v215, v169, s[60:61]
	v_cndmask_b32_e64 v170, v170, v215, s[62:63]
	v_cndmask_b32_e64 v171, v171, v215, s[64:65]
	v_cndmask_b32_e64 v173, v215, v173, s[68:69]
	v_cndmask_b32_e64 v172, v0, v172, s[68:69]
	v_cndmask_b32_e64 v174, v174, v215, s[70:71]
	v_cndmask_b32_e64 v175, v175, v215, s[72:73]

.LBB0_319:
	v_exp_f32_e32 v0, v160
	v_exp_f32_e32 v14, v161
	v_exp_f32_e32 v15, v162
	v_exp_f32_e32 v161, v163
	v_add_f32_e32 v160, 0, v0
	v_exp_f32_e32 v162, v164
	v_add_f32_e32 v160, v14, v160
	v_exp_f32_e32 v163, v165
	v_add_f32_e32 v160, v15, v160
	v_exp_f32_e32 v164, v166
	v_add_f32_e32 v160, v161, v160
	v_exp_f32_e32 v165, v167
	v_add_f32_e32 v160, v162, v160
	v_exp_f32_e32 v166, v168
	v_add_f32_e32 v160, v163, v160
	v_exp_f32_e32 v167, v169
	v_add_f32_e32 v160, v164, v160
	v_exp_f32_e32 v168, v170
	v_add_f32_e32 v160, v165, v160
	v_exp_f32_e32 v169, v171
	v_add_f32_e32 v160, v166, v160
	v_exp_f32_e32 v170, v172
	v_add_f32_e32 v160, v167, v160
	v_exp_f32_e32 v171, v173
	v_add_f32_e32 v160, v168, v160
	v_exp_f32_e32 v172, v174
	v_add_f32_e32 v160, v169, v160
	v_exp_f32_e32 v173, v175
	v_add_f32_e32 v160, v170, v160
	v_add_f32_e32 v160, v171, v160
	v_add_f32_e32 v160, v172, v160
	v_add_f32_e32 v192, v173, v160
	v_cvt_pk_bf16_f32 v160, v0, v14
	v_cvt_pk_bf16_f32 v161, v15, v161
	v_cvt_pk_bf16_f32 v162, v162, v163
	v_cvt_pk_bf16_f32 v163, v164, v165
	v_cvt_pk_bf16_f32 v164, v166, v167
	v_cvt_pk_bf16_f32 v165, v168, v169
	v_cvt_pk_bf16_f32 v166, v170, v171
	v_cvt_pk_bf16_f32 v167, v172, v173
	ds_read_b128 v[168:171], v218 offset:57888
	s_waitcnt lgkmcnt(3)
	v_mfma_f32_32x32x16_bf16 v[128:143], v[188:191], v[160:163], v[128:143]
	ds_read_b128 v[172:175], v218 offset:60416
	s_waitcnt lgkmcnt(3)
	v_mfma_f32_32x32x16_bf16 v[128:143], v[184:187], v[164:167], v[128:143]
	ds_read_b128 v[184:187], v218 offset:60448
	s_waitcnt lgkmcnt(3)
	v_mfma_f32_32x32x16_bf16 v[112:127], v[180:183], v[160:163], v[112:127]
	ds_read_b128 v[180:183], v218 offset:62976
	s_waitcnt lgkmcnt(3)
	v_mfma_f32_32x32x16_bf16 v[112:127], v[168:171], v[164:167], v[112:127]
	ds_read_b128 v[168:171], v218 offset:63008
	s_waitcnt lgkmcnt(3)
	v_mfma_f32_32x32x16_bf16 v[96:111], v[172:175], v[160:163], v[96:111]
	v_add_u32_e32 v0, 0x10000, v218
	ds_read_b128 v[172:175], v0
	s_waitcnt lgkmcnt(3)
	v_mfma_f32_32x32x16_bf16 v[96:111], v[184:187], v[164:167], v[96:111]
	v_add_u32_e32 v0, 0x10020, v218
	ds_read_b128 v[184:187], v0
	s_waitcnt lgkmcnt(3)
	v_mfma_f32_32x32x16_bf16 v[80:95], v[180:183], v[160:163], v[80:95]
	ds_read_b128 v[180:183], v226
	s_waitcnt lgkmcnt(3)
	v_mfma_f32_32x32x16_bf16 v[80:95], v[168:171], v[164:167], v[80:95]
	ds_read_b128 v[168:171], v227
	s_waitcnt lgkmcnt(3)
	v_mfma_f32_32x32x16_bf16 v[64:79], v[172:175], v[160:163], v[64:79]
	ds_read_b128 v[172:175], v228
	s_waitcnt lgkmcnt(3)
	v_mfma_f32_32x32x16_bf16 v[64:79], v[184:187], v[164:167], v[64:79]
	ds_read_b128 v[184:187], v229
	s_waitcnt lgkmcnt(3)
	v_mfma_f32_32x32x16_bf16 v[48:63], v[180:183], v[160:163], v[48:63]
	ds_read_b128 v[180:183], v230
	s_waitcnt lgkmcnt(3)
	v_mfma_f32_32x32x16_bf16 v[48:63], v[168:171], v[164:167], v[48:63]
	ds_read_b128 v[168:171], v231
	s_andn2_b64 vcc, exec, s[94:95]
	s_cbranch_vccnz .Lattn_w1_none
	s_waitcnt vmcnt(3)
	ds_write_b128 v207, v[2:5]
	s_waitcnt vmcnt(2)
	ds_write_b128 v207, v[6:9] offset:8704
	s_waitcnt vmcnt(1)
	ds_write2_b64 v208, v[10:11], v[12:13] offset0:128 offset1:130
	s_waitcnt vmcnt(0)
	ds_write2_b64 v209, v[176:177], v[178:179] offset0:128 offset1:130
	s_waitcnt lgkmcnt(7)
	v_mfma_f32_32x32x16_bf16 v[32:47], v[172:175], v[160:163], v[32:47]
	s_waitcnt lgkmcnt(6)
	v_mfma_f32_32x32x16_bf16 v[32:47], v[184:187], v[164:167], v[32:47]
	s_waitcnt lgkmcnt(5)
	v_mfma_f32_32x32x16_bf16 v[16:31], v[180:183], v[160:163], v[16:31]
	s_waitcnt lgkmcnt(4)
	v_mfma_f32_32x32x16_bf16 v[16:31], v[168:171], v[164:167], v[16:31]
	v_add_f32_e32 v235, v235, v192
	s_branch .LBB0_312
.Lattn_w1_none:
	s_waitcnt lgkmcnt(3)
	v_mfma_f32_32x32x16_bf16 v[32:47], v[172:175], v[160:163], v[32:47]
	s_waitcnt lgkmcnt(2)
	v_mfma_f32_32x32x16_bf16 v[32:47], v[184:187], v[164:167], v[32:47]
	s_waitcnt lgkmcnt(1)
	v_mfma_f32_32x32x16_bf16 v[16:31], v[180:183], v[160:163], v[16:31]
	s_waitcnt lgkmcnt(0)
	v_mfma_f32_32x32x16_bf16 v[16:31], v[168:171], v[164:167], v[16:31]
	v_add_f32_e32 v235, v235, v192
	s_branch .LBB0_312

.LBB0_312:
	s_add_u32 s26, s26, 0x8000
	s_addc_u32 s27, s27, 0
	v_lshl_add_u64 v[200:201], v[200:201], 0, s[20:21]
	s_and_b64 vcc, exec, s[30:31]
	s_waitcnt lgkmcnt(0)
	s_barrier
	s_cbranch_vccnz .LBB0_320
	s_mov_b32 s97, s78
	s_branch .LBB0_298
.LBB0_320:
	v_mov_b32_e32 v0, v235
	s_nop 1
	v_permlane32_swap_b32_e32 v235, v0
	v_add_f32_e32 v0, v235, v0
	s_waitcnt vmcnt(3)
	v_div_scale_f32 v2, s[26:27], v0, v0, 1.0
	v_rcp_f32_e32 v3, v2
	v_readlane_b32 s15, v251, 62
	v_readlane_b32 s26, v251, 63
	v_mbcnt_lo_u32_b32 v144, -1, 0
	v_mbcnt_hi_u32_b32 v144, -1, v144
	v_fma_f32 v4, -v2, v3, 1.0
	v_fmac_f32_e32 v3, v4, v3
	v_div_scale_f32 v4, vcc, 1.0, v0, 1.0
	v_mul_f32_e32 v5, v4, v3
	s_waitcnt vmcnt(2)
	v_fma_f32 v6, -v2, v5, v4
	v_fmac_f32_e32 v5, v6, v3
	v_fma_f32 v2, -v2, v5, v4
	v_div_fmas_f32 v2, v2, v3, v5
	v_div_fixup_f32 v0, v2, v0, 1.0
	v_lshl_add_u32 v2, v144, 2, s15
	v_readlane_b32 s27, v252, 0
	s_and_b64 vcc, exec, s[26:27]
	s_waitcnt vmcnt(1)
	v_add_u32_e32 v10, 0, v2
	s_cbranch_vccz .LBB0_322
	v_mul_f32_e32 v2, v204, v0
	v_mul_f32_e32 v3, v128, v2
	v_mul_f32_e32 v4, v129, v2
	ds_write2st64_b32 v10, v3, v4 offset1:1
	v_mul_f32_e32 v3, v130, v2
	v_mul_f32_e32 v4, v131, v2
	ds_write2st64_b32 v10, v3, v4 offset0:2 offset1:3
	v_mul_f32_e32 v3, v132, v2
	v_mul_f32_e32 v4, v133, v2
	ds_write2st64_b32 v10, v3, v4 offset0:4 offset1:5
	v_mul_f32_e32 v3, v134, v2
	v_mul_f32_e32 v4, v135, v2
	ds_write2st64_b32 v10, v3, v4 offset0:6 offset1:7
	v_mul_f32_e32 v3, v136, v2
	v_mul_f32_e32 v4, v137, v2
	ds_write2st64_b32 v10, v3, v4 offset0:8 offset1:9
	v_mul_f32_e32 v3, v138, v2
	v_mul_f32_e32 v4, v139, v2
	ds_write2st64_b32 v10, v3, v4 offset0:10 offset1:11
	v_mul_f32_e32 v3, v140, v2
	v_mul_f32_e32 v4, v141, v2
	ds_write2st64_b32 v10, v3, v4 offset0:12 offset1:13
	v_mul_f32_e32 v3, v142, v2
	v_mul_f32_e32 v4, v143, v2
	ds_write2st64_b32 v10, v3, v4 offset0:14 offset1:15
	v_mul_f32_e32 v3, v112, v2
	v_mul_f32_e32 v4, v113, v2
	ds_write2st64_b32 v10, v3, v4 offset0:16 offset1:17
	v_mul_f32_e32 v3, v114, v2
	v_mul_f32_e32 v4, v115, v2
	ds_write2st64_b32 v10, v3, v4 offset0:18 offset1:19
	v_mul_f32_e32 v3, v116, v2
	v_mul_f32_e32 v4, v117, v2
	ds_write2st64_b32 v10, v3, v4 offset0:20 offset1:21
	v_mul_f32_e32 v3, v118, v2
	v_mul_f32_e32 v4, v119, v2
	ds_write2st64_b32 v10, v3, v4 offset0:22 offset1:23
	v_mul_f32_e32 v3, v120, v2
	v_mul_f32_e32 v4, v121, v2
	ds_write2st64_b32 v10, v3, v4 offset0:24 offset1:25
	v_mul_f32_e32 v3, v122, v2
	v_mul_f32_e32 v4, v123, v2
	ds_write2st64_b32 v10, v3, v4 offset0:26 offset1:27
	v_mul_f32_e32 v3, v124, v2
	v_mul_f32_e32 v4, v125, v2
	ds_write2st64_b32 v10, v3, v4 offset0:28 offset1:29
	v_mul_f32_e32 v3, v126, v2
	v_mul_f32_e32 v4, v127, v2
	ds_write2st64_b32 v10, v3, v4 offset0:30 offset1:31
	v_mul_f32_e32 v3, v96, v2
	v_mul_f32_e32 v4, v97, v2
	ds_write2st64_b32 v10, v3, v4 offset0:32 offset1:33
	v_mul_f32_e32 v3, v98, v2
	v_mul_f32_e32 v4, v99, v2
	ds_write2st64_b32 v10, v3, v4 offset0:34 offset1:35
	v_mul_f32_e32 v3, v100, v2
	v_mul_f32_e32 v4, v101, v2
	ds_write2st64_b32 v10, v3, v4 offset0:36 offset1:37
	v_mul_f32_e32 v3, v102, v2
	v_mul_f32_e32 v4, v103, v2
	ds_write2st64_b32 v10, v3, v4 offset0:38 offset1:39
	v_mul_f32_e32 v3, v104, v2
	v_mul_f32_e32 v4, v105, v2
	ds_write2st64_b32 v10, v3, v4 offset0:40 offset1:41
	v_mul_f32_e32 v3, v106, v2
	v_mul_f32_e32 v4, v107, v2
	ds_write2st64_b32 v10, v3, v4 offset0:42 offset1:43
	v_mul_f32_e32 v3, v108, v2
	v_mul_f32_e32 v4, v109, v2
	ds_write2st64_b32 v10, v3, v4 offset0:44 offset1:45
	v_mul_f32_e32 v3, v110, v2
	v_mul_f32_e32 v4, v111, v2
	ds_write2st64_b32 v10, v3, v4 offset0:46 offset1:47
	v_mul_f32_e32 v3, v80, v2
	v_mul_f32_e32 v4, v81, v2
	ds_write2st64_b32 v10, v3, v4 offset0:48 offset1:49
	v_mul_f32_e32 v3, v82, v2
	v_mul_f32_e32 v4, v83, v2
	ds_write2st64_b32 v10, v3, v4 offset0:50 offset1:51
	v_mul_f32_e32 v3, v84, v2
	v_mul_f32_e32 v4, v85, v2
	ds_write2st64_b32 v10, v3, v4 offset0:52 offset1:53
	v_mul_f32_e32 v3, v86, v2
	v_mul_f32_e32 v4, v87, v2
	ds_write2st64_b32 v10, v3, v4 offset0:54 offset1:55
	v_mul_f32_e32 v3, v88, v2
	v_mul_f32_e32 v4, v89, v2
	ds_write2st64_b32 v10, v3, v4 offset0:56 offset1:57
	v_mul_f32_e32 v3, v90, v2
	v_mul_f32_e32 v4, v91, v2
	ds_write2st64_b32 v10, v3, v4 offset0:58 offset1:59
	v_mul_f32_e32 v3, v92, v2
	v_mul_f32_e32 v4, v93, v2
	ds_write2st64_b32 v10, v3, v4 offset0:60 offset1:61
	v_mul_f32_e32 v3, v94, v2
	v_mul_f32_e32 v4, v95, v2
	ds_write2st64_b32 v10, v3, v4 offset0:62 offset1:63
	v_mul_f32_e32 v3, v64, v2
	v_mul_f32_e32 v4, v65, v2
	ds_write2st64_b32 v10, v3, v4 offset0:64 offset1:65
	v_mul_f32_e32 v3, v66, v2
	v_mul_f32_e32 v4, v67, v2
	ds_write2st64_b32 v10, v3, v4 offset0:66 offset1:67
	v_mul_f32_e32 v3, v68, v2
	v_mul_f32_e32 v4, v69, v2
	ds_write2st64_b32 v10, v3, v4 offset0:68 offset1:69
	v_mul_f32_e32 v3, v70, v2
	v_mul_f32_e32 v4, v71, v2
	ds_write2st64_b32 v10, v3, v4 offset0:70 offset1:71
	v_mul_f32_e32 v3, v72, v2
	v_mul_f32_e32 v4, v73, v2
	ds_write2st64_b32 v10, v3, v4 offset0:72 offset1:73
	v_mul_f32_e32 v3, v74, v2
	v_mul_f32_e32 v4, v75, v2
	ds_write2st64_b32 v10, v3, v4 offset0:74 offset1:75
	v_mul_f32_e32 v3, v76, v2
	v_mul_f32_e32 v4, v77, v2
	ds_write2st64_b32 v10, v3, v4 offset0:76 offset1:77
	v_mul_f32_e32 v3, v78, v2
	v_mul_f32_e32 v4, v79, v2
	ds_write2st64_b32 v10, v3, v4 offset0:78 offset1:79
	v_mul_f32_e32 v3, v48, v2
	v_mul_f32_e32 v4, v49, v2
	ds_write2st64_b32 v10, v3, v4 offset0:80 offset1:81
	v_mul_f32_e32 v3, v50, v2
	v_mul_f32_e32 v4, v51, v2
	ds_write2st64_b32 v10, v3, v4 offset0:82 offset1:83
	v_mul_f32_e32 v3, v52, v2
	v_mul_f32_e32 v4, v53, v2
	ds_write2st64_b32 v10, v3, v4 offset0:84 offset1:85
	v_mul_f32_e32 v3, v54, v2
	v_mul_f32_e32 v4, v55, v2
	ds_write2st64_b32 v10, v3, v4 offset0:86 offset1:87
	v_mul_f32_e32 v3, v56, v2
	v_mul_f32_e32 v4, v57, v2
	ds_write2st64_b32 v10, v3, v4 offset0:88 offset1:89
	v_mul_f32_e32 v3, v58, v2
	v_mul_f32_e32 v4, v59, v2
	ds_write2st64_b32 v10, v3, v4 offset0:90 offset1:91
	v_mul_f32_e32 v3, v60, v2
	v_mul_f32_e32 v4, v61, v2
	ds_write2st64_b32 v10, v3, v4 offset0:92 offset1:93
	v_mul_f32_e32 v3, v62, v2
	v_mul_f32_e32 v4, v63, v2
	ds_write2st64_b32 v10, v3, v4 offset0:94 offset1:95
	v_mul_f32_e32 v3, v32, v2
	v_mul_f32_e32 v4, v33, v2
	ds_write2st64_b32 v10, v3, v4 offset0:96 offset1:97
	v_mul_f32_e32 v3, v34, v2
	v_mul_f32_e32 v4, v35, v2
	ds_write2st64_b32 v10, v3, v4 offset0:98 offset1:99
	v_mul_f32_e32 v3, v36, v2
	v_mul_f32_e32 v4, v37, v2
	ds_write2st64_b32 v10, v3, v4 offset0:100 offset1:101
	v_mul_f32_e32 v3, v38, v2
	v_mul_f32_e32 v4, v39, v2
	ds_write2st64_b32 v10, v3, v4 offset0:102 offset1:103
	v_mul_f32_e32 v3, v40, v2
	v_mul_f32_e32 v4, v41, v2
	ds_write2st64_b32 v10, v3, v4 offset0:104 offset1:105
	v_mul_f32_e32 v3, v42, v2
	v_mul_f32_e32 v4, v43, v2
	ds_write2st64_b32 v10, v3, v4 offset0:106 offset1:107
	v_mul_f32_e32 v3, v44, v2
	v_mul_f32_e32 v4, v45, v2
	ds_write2st64_b32 v10, v3, v4 offset0:108 offset1:109
	v_mul_f32_e32 v3, v46, v2
	v_mul_f32_e32 v4, v47, v2
	ds_write2st64_b32 v10, v3, v4 offset0:110 offset1:111
	v_mul_f32_e32 v3, v16, v2
	v_mul_f32_e32 v4, v17, v2
	ds_write2st64_b32 v10, v3, v4 offset0:112 offset1:113
	v_mul_f32_e32 v3, v18, v2
	v_mul_f32_e32 v4, v19, v2
	ds_write2st64_b32 v10, v3, v4 offset0:114 offset1:115
	v_mul_f32_e32 v3, v20, v2
	v_mul_f32_e32 v4, v21, v2
	ds_write2st64_b32 v10, v3, v4 offset0:116 offset1:117
	v_mul_f32_e32 v3, v22, v2
	v_mul_f32_e32 v4, v23, v2
	ds_write2st64_b32 v10, v3, v4 offset0:118 offset1:119
	v_mul_f32_e32 v3, v24, v2
	v_mul_f32_e32 v4, v25, v2
	ds_write2st64_b32 v10, v3, v4 offset0:120 offset1:121
	v_mul_f32_e32 v3, v26, v2
	v_mul_f32_e32 v4, v27, v2
	ds_write2st64_b32 v10, v3, v4 offset0:122 offset1:123
	v_mul_f32_e32 v3, v28, v2
	v_mul_f32_e32 v4, v29, v2
	ds_write2st64_b32 v10, v3, v4 offset0:124 offset1:125
	v_mul_f32_e32 v3, v30, v2
	v_mul_f32_e32 v2, v31, v2
	ds_write2st64_b32 v10, v3, v2 offset0:126 offset1:127
